# differential attention: waves 4-7 issue their half of the next stage's K/V LDS-DMA between the two key blocks instead of at the stage top (DMA issue overlaps the partner wave's MFMAs, natural stagger)
# baseline (speedup 1.0000x reference)
; template <bool SB>
; __device__ __forceinline__ void attn_unit(LAS unsigned char* lds, const bf16_t* qkv, bf16_t* merged, int b, int gi, int qb,
;                                           const float* gnorm, float lam, float outscale, const float* rel_bias) {
;     ...
;     int kt = ktmax, st = 0;
;     ISSUE_STAGE(kt, 0);
;     for (;;) {
;         asm volatile("s_waitcnt vmcnt(0)" ::: "memory");
;         __syncthreads();
;         if (SB && kt != ktmax) { const int f = flags[(st ^ 1) * 8 + (lane & 7)]; if (__all(f != 0)) break; }
;         if (kt > 0) ISSUE_STAGE(kt - 1, st ^ 1);
.LBB0_151:
	s_mov_b64 s[94:95], s[4:5]
	s_cmp_eq_u32 s75, 1
	s_cbranch_scc0 .Ldma_g0_0
	s_lshl_b32 s81, s80, 16
	s_branch .LBB0_153

; template <bool SB>
; __device__ __forceinline__ void attn_unit(LAS unsigned char* lds, const bf16_t* qkv, bf16_t* merged, int b, int gi, int qb,
;                                           const float* gnorm, float lam, float outscale, const float* rel_bias) {
;     ...
;         if (kt > 0) ISSUE_STAGE(kt - 1, st ^ 1);
.LBB0_193:
	s_cmp_eq_u32 s75, 1
	s_cbranch_scc0 .Ldma_skip_0
	s_andn2_b64 vcc, exec, s[94:95]
	s_cbranch_vccnz .Ldma_skip_0
	s_lshl_b64 s[4:5], s[6:7], 6
	s_add_u32 s4, s4, s40
	s_addc_u32 s5, s5, s41
	s_mulk_i32 s5, 0x3000
	s_mul_hi_u32 s81, s4, 0x3000
	s_add_i32 s81, s81, s5
	s_mulk_i32 s4, 0x3000
	s_add_u32 s4, s22, s4
	s_addc_u32 s5, s23, s81
	s_lshl_b32 s81, s80, 16
	s_xor_b32 s82, s81, 0x10000
	v_lshl_add_u64 v[2:3], v[198:199], 1, s[4:5]
	s_add_i32 s83, s82, s50
	v_lshl_add_u64 v[4:5], v[196:197], 1, s[4:5]
	s_mov_b32 s5, m0
	s_mov_b32 m0, s83
	s_nop 0
	global_load_lds_dwordx4 v[2:3], off
	s_mov_b32 m0, s5
	s_add_i32 s4, s82, s51
	s_mov_b32 s5, m0
	s_mov_b32 m0, s4
	s_nop 0
	global_load_lds_dwordx4 v[4:5], off
	s_mov_b32 m0, s5
	v_lshl_add_u64 v[6:7], v[2:3], 0, s[28:29]
	s_add_i32 s5, s83, 0x2000
	s_mov_b32 s82, m0
	s_mov_b32 m0, s5
	s_nop 0
	global_load_lds_dwordx4 v[6:7], off
	s_mov_b32 m0, s82
	v_lshl_add_u64 v[6:7], v[4:5], 0, s[28:29]
	s_add_i32 s5, s4, 0x2000
	s_mov_b32 s82, m0
	s_mov_b32 m0, s5
	s_nop 0
	global_load_lds_dwordx4 v[6:7], off
	s_mov_b32 m0, s82
	v_lshl_add_u64 v[6:7], v[2:3], 0, s[30:31]
	s_add_i32 s5, s83, 0x4000
	s_mov_b32 s82, m0
	s_mov_b32 m0, s5
	s_nop 0
	global_load_lds_dwordx4 v[6:7], off
	s_mov_b32 m0, s82
	v_lshl_add_u64 v[6:7], v[4:5], 0, s[30:31]
	s_add_i32 s5, s4, 0x4000
	s_mov_b32 s82, m0
	s_mov_b32 m0, s5
	s_nop 0
	global_load_lds_dwordx4 v[6:7], off
	s_mov_b32 m0, s82
	v_lshl_add_u64 v[2:3], v[2:3], 0, s[34:35]
	s_add_i32 s5, s83, 0x6000
	s_mov_b32 s82, m0
	s_mov_b32 m0, s5
	s_nop 0
	global_load_lds_dwordx4 v[2:3], off
	s_mov_b32 m0, s82
	v_lshl_add_u64 v[2:3], v[4:5], 0, s[34:35]
	s_addk_i32 s4, 0x6000
	s_mov_b32 s5, m0
	s_mov_b32 m0, s4
	s_nop 0
	global_load_lds_dwordx4 v[2:3], off
	s_mov_b32 m0, s5

; __global__ void __launch_bounds__(512, 2) fwd_mega(Args a) {
	.amdhsa_kernel _Z8fwd_mega4Args
		.amdhsa_group_segment_fixed_size 0
		.amdhsa_private_segment_fixed_size 0
		.amdhsa_kernarg_size 424
		.amdhsa_user_sgpr_count 2
		.amdhsa_user_sgpr_dispatch_ptr 0
		.amdhsa_user_sgpr_queue_ptr 0
		.amdhsa_user_sgpr_kernarg_segment_ptr 1
		.amdhsa_user_sgpr_dispatch_id 0
		.amdhsa_user_sgpr_kernarg_preload_length 0
		.amdhsa_user_sgpr_kernarg_preload_offset 0
		.amdhsa_user_sgpr_private_segment_size 0
		.amdhsa_uses_dynamic_stack 0
		.amdhsa_enable_private_segment 0
		.amdhsa_system_sgpr_workgroup_id_x 1
		.amdhsa_system_sgpr_workgroup_id_y 0
		.amdhsa_system_sgpr_workgroup_id_z 0
		.amdhsa_system_sgpr_workgroup_info 0
		.amdhsa_system_vgpr_workitem_id 2
		.amdhsa_next_free_vgpr 254
		.amdhsa_next_free_sgpr 96
		.amdhsa_accum_offset 256
		.amdhsa_reserve_vcc 1
		.amdhsa_float_round_mode_32 0
		.amdhsa_float_round_mode_16_64 0
		.amdhsa_float_denorm_mode_32 3
		.amdhsa_float_denorm_mode_16_64 3
		.amdhsa_dx10_clamp 1
		.amdhsa_ieee_mode 1
		.amdhsa_fp16_overflow 0
		.amdhsa_tg_split 0
		.amdhsa_exception_fp_ieee_invalid_op 0
		.amdhsa_exception_fp_denorm_src 0
		.amdhsa_exception_fp_ieee_div_zero 0
		.amdhsa_exception_fp_ieee_overflow 0
		.amdhsa_exception_fp_ieee_underflow 0
		.amdhsa_exception_fp_ieee_inexact 0
		.amdhsa_exception_int_div_zero 0
	.end_amdhsa_kernel

; __global__ void __launch_bounds__(512, 2) fwd_mega(Args a) {
amdhsa.kernels:
  - .agpr_count:     0
    .args:
      - .offset:         0
        .size:           168
        .value_kind:     by_value
      - .offset:         168
        .size:           4
        .value_kind:     hidden_block_count_x
      - .offset:         172
        .size:           4
        .value_kind:     hidden_block_count_y
      - .offset:         176
        .size:           4
        .value_kind:     hidden_block_count_z
      - .offset:         180
        .size:           2
        .value_kind:     hidden_group_size_x
      - .offset:         182
        .size:           2
        .value_kind:     hidden_group_size_y
      - .offset:         184
        .size:           2
        .value_kind:     hidden_group_size_z
      - .offset:         186
        .size:           2
        .value_kind:     hidden_remainder_x
      - .offset:         188
        .size:           2
        .value_kind:     hidden_remainder_y
      - .offset:         190
        .size:           2
        .value_kind:     hidden_remainder_z
      - .offset:         208
        .size:           8
        .value_kind:     hidden_global_offset_x
      - .offset:         216
        .size:           8
        .value_kind:     hidden_global_offset_y
      - .offset:         224
        .size:           8
        .value_kind:     hidden_global_offset_z
      - .offset:         232
        .size:           2
        .value_kind:     hidden_grid_dims
      - .offset:         256
        .size:           8
        .value_kind:     hidden_multigrid_sync_arg
      - .offset:         288
        .size:           4
        .value_kind:     hidden_dynamic_lds_size
    .group_segment_fixed_size: 0
    .kernarg_segment_align: 8
    .kernarg_segment_size: 424
    .language:       OpenCL C
    .language_version:
      - 2
      - 0
    .max_flat_workgroup_size: 512
    .name:           _Z8fwd_mega4Args
    .private_segment_fixed_size: 0
    .sgpr_count:     102
    .sgpr_spill_count: 0
    .symbol:         _Z8fwd_mega4Args.kd
    .uniform_work_group_size: 1
    .uses_dynamic_stack: false
    .vgpr_count:     254
    .vgpr_spill_count: 0
    .wavefront_size: 64
